# topgen kernel plus FFN in-projection tile decode: the runtime division by the m-group height (always 8 for 128 m-tiles) replaced by shifts, 27 scalar/vector instructions incl. a rcp and readfirstlane
# speedup vs baseline: 1.0159x; 1.0159x over previous
;     __host__ __device__ bool next(int i, Unit& u) const {
;         const long L = (long)i * G + c; if (L >= nwg) return false;
;         int wgid = (int)L; { const int q = nwg / NXCD, r = nwg % NXCD, xcd = wgid % NXCD, off = wgid / NXCD; wgid = (xcd < r ? xcd * (q + 1) : r * (q + 1) + (xcd - r) * q) + off; }
;         const int nig = WGM * nN, gid = wgid / nig, fm = gid * WGM, gsz = (nM - fm) < WGM ? (nM - fm) : WGM;
;         u.pm = fm + ((wgid % nig) % gsz); u.pn = (wgid % nig) / gsz; u.sw = 0; return true;
.LBB0_107:
	s_add_i32 s58, s58, 1
	s_mul_i32 s4, s58, s36
	s_mul_hi_u32 s5, s58, s28
	s_add_i32 s5, s5, s4
	s_mul_i32 s4, s58, s28
	s_add_u32 s18, s4, s2
	s_addc_u32 s19, s5, s33
	v_cmp_gt_i64_e32 vcc, s[18:19], v[164:165]
	v_cmp_lt_i64_e64 s[4:5], s[18:19], v[162:163]
	s_cbranch_vccnz .LBB0_109
	s_ashr_i32 s14, s18, 31
	s_lshr_b32 s14, s14, 29
	s_add_i32 s14, s18, s14
	s_ashr_i32 s15, s14, 3
	s_and_b32 s14, s14, -8
	s_sub_i32 s14, s18, s14
	s_cmp_lt_i32 s14, 0
	s_movk_i32 s16, 0x161
	s_cselect_b32 s16, s16, 0x160
	s_mul_i32 s14, s14, s16
	s_add_i32 s14, s14, s15
	s_mul_hi_i32 s15, s14, 0x2e8ba2e9
	s_lshr_b32 s16, s15, 31
	s_ashr_i32 s15, s15, 5
	s_add_i32 s15, s15, s16
	s_lshl_b32 s16, s15, 3
	s_mulk_i32 s15, 0xb0
	s_sub_i32 s15, s14, s15
	s_lshr_b32 s14, s15, 3
	s_lshl_b32 s17, s14, 3
	s_sub_i32 s15, s15, s17
	s_add_i32 s16, s16, s15
